# end-of-step wait selection of the second attention step: the common case branches straight to the counted wait and barrier (shortened wave-uniform branch chain)
# baseline (speedup 1.0000x reference)
.Lfastw_1:
	s_waitcnt vmcnt(4) lgkmcnt(0)
	s_barrier
